# v40 + W_out and FFN2-down GEMM epilogues touch the cache lines of all 16 read-modify-write groups up front
# baseline (speedup 1.0000x reference)
; __device__ __forceinline__ unsigned pkbf(float lo, float hi) { return pg8::cvt_pk_bf16(lo, hi); }
; __device__ __forceinline__ void unpack8bf(const u32x4 w, float* f) { f[0] = bflo(w.x); f[1] = bfhi(w.x); f[2] = bflo(w.y); f[3] = bfhi(w.y); f[4] = bflo(w.z); f[5] = bfhi(w.z); f[6] = bflo(w.w); f[7] = bfhi(w.w); }
;     __device__ __forceinline__ void operator()(AccRef acc, const Unit& u, int wr, int wc, int fr, int fq) const {
;         asm volatile("" : "+v"(fr), "+v"(fq));
;         const int row0 = u.pm * 256 + wr * 64 + fr, col0 = u.pn * 256 + wc * 32 + 8 * fq;
;         const float* xb = (u.pm * 256 < TP) ? xp : xs - (size_t)TP * DM;
; #pragma unroll
;         for (int ai = 0; ai < 2; ++ai)
; #pragma unroll
;             for (int m = 0; m < 4; ++m)
; #pragma unroll
;                 for (int bj = 0; bj < 2; ++bj) {
;                     const size_t off = (size_t)(row0 + ai * 128 + m * 16) * DM + col0 + bj * 128;
;                     const f32x4 x0 = *(const f32x4*)(xb + off), x1 = *(const f32x4*)(xb + off + 4);
;                     const u32x4 dw = *(const u32x4*)(D1 + off); float d[8]; unpack8bf(dw, d);
;                     float o[8];
; #pragma unroll
;                     for (int e = 0; e < 4; ++e) { o[e] = x0[e] + d[e] + acc[ai][bj][m][0][e]; o[4 + e] = x1[e] + d[4 + e] + acc[ai][bj][m][1][e]; }
;                     u32x4 w; w.x = pkbf(o[0], o[1]); w.y = pkbf(o[2], o[3]); w.z = pkbf(o[4], o[5]); w.w = pkbf(o[6], o[7]);
;                     *(u32x4*)(D1 + off) = w;
;                 }
;     }
.LBB0_1244:
	v_mov_b32_e32 v147, v148
	v_mov_b32_e32 v146, v129
	s_lshl_b32 s4, s58, 8
	s_add_i32 s4, s4, s68
	v_add_u32_e32 v146, s4, v146
	s_lshl_b32 s4, s78, 8
	s_or_b32 s4, s4, s69
	v_lshl_add_u32 v154, v147, 3, s4
	v_ashrrev_i32_e32 v147, 31, v146
	v_ashrrev_i32_e32 v155, 31, v154
	v_lshlrev_b64 v[146:147], 10, v[146:147]
	v_readlane_b32 s4, v237, 5
	v_lshl_add_u64 v[146:147], v[146:147], 0, v[154:155]
	s_cmpk_lt_i32 s58, 0x80
	v_readlane_b32 s5, v237, 6
	v_lshl_add_u64 v[162:163], v[146:147], 1, s[30:31]
	s_cselect_b32 s5, s5, s72
	s_cselect_b32 s4, s4, s71
	global_load_dwordx4 v[154:157], v[162:163], off
	v_lshl_add_u64 v[172:173], v[146:147], 2, s[4:5]
	global_load_dwordx4 v[158:161], v[172:173], off nt
	global_load_dwordx4 v[168:171], v[172:173], off offset:16 nt
	s_mov_b64 s[98:99], 0x8000
	s_mov_b64 s[100:101], 0x28000
	v_mov_b64_e32 v[180:181], v[162:163]
	v_mov_b64_e32 v[182:183], v[172:173]
	global_load_dwordx4 v[176:179], v[180:181], off offset:256
	v_lshl_add_u64 v[180:181], v[180:181], 0, s[98:99]
	global_load_dwordx4 v[176:179], v[180:181], off
	global_load_dwordx4 v[176:179], v[180:181], off offset:256
	v_lshl_add_u64 v[180:181], v[180:181], 0, s[98:99]
	global_load_dwordx4 v[176:179], v[180:181], off
	global_load_dwordx4 v[176:179], v[180:181], off offset:256
	v_lshl_add_u64 v[180:181], v[180:181], 0, s[98:99]
	global_load_dwordx4 v[176:179], v[180:181], off
	global_load_dwordx4 v[176:179], v[180:181], off offset:256
	v_lshl_add_u64 v[180:181], v[180:181], 0, s[100:101]
	global_load_dwordx4 v[176:179], v[180:181], off
	global_load_dwordx4 v[176:179], v[180:181], off offset:256
	v_lshl_add_u64 v[180:181], v[180:181], 0, s[98:99]
	global_load_dwordx4 v[176:179], v[180:181], off
	global_load_dwordx4 v[176:179], v[180:181], off offset:256
	v_lshl_add_u64 v[180:181], v[180:181], 0, s[98:99]
	global_load_dwordx4 v[176:179], v[180:181], off
	global_load_dwordx4 v[176:179], v[180:181], off offset:256
	v_lshl_add_u64 v[180:181], v[180:181], 0, s[98:99]
	global_load_dwordx4 v[176:179], v[180:181], off
	global_load_dwordx4 v[176:179], v[180:181], off offset:256
	global_load_dwordx4 v[176:179], v[182:183], off offset:512 nt
	v_lshl_add_u64 v[182:183], s[98:99], 1, v[182:183]
	global_load_dwordx4 v[176:179], v[182:183], off nt
	global_load_dwordx4 v[176:179], v[182:183], off offset:512 nt
	v_lshl_add_u64 v[182:183], s[98:99], 1, v[182:183]
	global_load_dwordx4 v[176:179], v[182:183], off nt
	global_load_dwordx4 v[176:179], v[182:183], off offset:512 nt
	v_lshl_add_u64 v[182:183], s[98:99], 1, v[182:183]
	global_load_dwordx4 v[176:179], v[182:183], off nt
	global_load_dwordx4 v[176:179], v[182:183], off offset:512 nt
	v_lshl_add_u64 v[182:183], s[100:101], 1, v[182:183]
	global_load_dwordx4 v[176:179], v[182:183], off nt
	global_load_dwordx4 v[176:179], v[182:183], off offset:512 nt
	v_lshl_add_u64 v[182:183], s[98:99], 1, v[182:183]
	global_load_dwordx4 v[176:179], v[182:183], off nt
	global_load_dwordx4 v[176:179], v[182:183], off offset:512 nt
	v_lshl_add_u64 v[182:183], s[98:99], 1, v[182:183]
	global_load_dwordx4 v[176:179], v[182:183], off nt
	global_load_dwordx4 v[176:179], v[182:183], off offset:512 nt
	v_lshl_add_u64 v[182:183], s[98:99], 1, v[182:183]
	global_load_dwordx4 v[176:179], v[182:183], off nt
	global_load_dwordx4 v[176:179], v[182:183], off offset:512 nt
	v_readlane_b32 s10, v237, 11
	v_readlane_b32 s11, v237, 12
	s_mov_b64 s[10:11], 0x4000
	s_and_b64 vcc, exec, s[46:47]
	v_readlane_b32 s6, v237, 7
	v_readlane_b32 s7, v237, 8
	v_readlane_b32 s8, v237, 9
	v_readlane_b32 s9, v237, 10
	v_readlane_b32 s12, v237, 13
	v_readlane_b32 s13, v237, 14
	v_readlane_b32 s14, v237, 15
	v_readlane_b32 s15, v237, 16
	v_readlane_b32 s16, v237, 17
	v_readlane_b32 s17, v237, 18
	v_readlane_b32 s18, v237, 19
	v_readlane_b32 s19, v237, 20
	s_waitcnt vmcnt(0)
	v_lshlrev_b32_e32 v153, 16, v154
	v_and_b32_e32 v154, 0xffff0000, v154
	v_lshlrev_b32_e32 v165, 16, v155
	v_and_b32_e32 v155, 0xffff0000, v155
	v_lshlrev_b32_e32 v166, 16, v156
	v_and_b32_e32 v156, 0xffff0000, v156
	v_lshlrev_b32_e32 v174, 16, v157
	v_and_b32_e32 v157, 0xffff0000, v157
	v_add_f32_e32 v153, v158, v153
	v_add_f32_e32 v158, v168, v166
	v_add_f32_e32 v154, v159, v154
	v_add_f32_e32 v156, v169, v156
	v_add_f32_e32 v159, v160, v165
	v_add_f32_e32 v160, v170, v174
	v_add_f32_e32 v155, v161, v155
	v_add_f32_e32 v157, v171, v157
	v_add_f32_e32 v120, v120, v153
	v_add_f32_e32 v124, v124, v158
	v_add_f32_e32 v121, v121, v154
	v_add_f32_e32 v125, v125, v156
	v_add_f32_e32 v122, v122, v159
	v_add_f32_e32 v126, v126, v160
	v_add_f32_e32 v123, v123, v155
	v_add_f32_e32 v127, v127, v157
	v_cvt_pk_bf16_f32 v120, v120, v121
	v_cvt_pk_bf16_f32 v121, v122, v123
	v_cvt_pk_bf16_f32 v122, v124, v125
	v_cvt_pk_bf16_f32 v123, v126, v127
	global_load_dwordx4 v[124:127], v[162:163], off offset:256
	v_lshl_add_u64 v[158:159], v[146:147], 0, s[10:11]
	global_store_dwordx4 v[162:163], v[120:123], off
	global_load_dwordx4 v[120:123], v[172:173], off offset:512 nt
	s_nop 0
	global_load_dwordx4 v[154:157], v[172:173], off offset:528 nt
	v_lshl_add_u64 v[160:161], v[158:159], 1, s[30:31]
	s_waitcnt vmcnt(0)
; __device__ __forceinline__ unsigned pkbf(float lo, float hi) { return pg8::cvt_pk_bf16(lo, hi); }
; __device__ __forceinline__ void unpack8bf(const u32x4 w, float* f) { f[0] = bflo(w.x); f[1] = bfhi(w.x); f[2] = bflo(w.y); f[3] = bfhi(w.y); f[4] = bflo(w.z); f[5] = bfhi(w.z); f[6] = bflo(w.w); f[7] = bfhi(w.w); }
;     __device__ __forceinline__ void operator()(AccRef acc, const Unit& u, int wr, int wc, int fr, int fq) const {
;     ...
;                     const size_t off = (size_t)(row0 + ai * 128 + m * 16) * DM + col0 + bj * 128;
;                     const f32x4 x0 = *(const f32x4*)(xb + off), x1 = *(const f32x4*)(xb + off + 4);
;                     const u32x4 dw = *(const u32x4*)(D1 + off); float d[8]; unpack8bf(dw, d);
;                     float o[8];
; #pragma unroll
;                     for (int e = 0; e < 4; ++e) { o[e] = x0[e] + d[e] + acc[ai][bj][m][0][e]; o[4 + e] = x1[e] + d[4 + e] + acc[ai][bj][m][1][e]; }
;                     u32x4 w; w.x = pkbf(o[0], o[1]); w.y = pkbf(o[2], o[3]); w.z = pkbf(o[4], o[5]); w.w = pkbf(o[6], o[7]);
;                     *(u32x4*)(D1 + off) = w;
	v_lshlrev_b32_e32 v153, 16, v124
	v_and_b32_e32 v124, 0xffff0000, v124
	v_lshlrev_b32_e32 v165, 16, v125
	v_and_b32_e32 v125, 0xffff0000, v125
	v_lshlrev_b32_e32 v166, 16, v126
	v_and_b32_e32 v126, 0xffff0000, v126
	v_lshlrev_b32_e32 v168, 16, v127
	v_and_b32_e32 v127, 0xffff0000, v127
	v_add_f32_e32 v120, v120, v153
	v_add_f32_e32 v153, v154, v166
	v_add_f32_e32 v121, v121, v124
	v_add_f32_e32 v124, v155, v126
	v_add_f32_e32 v122, v122, v165
	v_add_f32_e32 v126, v156, v168
	v_add_f32_e32 v123, v123, v125
	v_add_f32_e32 v125, v157, v127
	v_add_f32_e32 v116, v116, v120
	v_add_f32_e32 v120, v112, v153
	v_add_f32_e32 v112, v117, v121
	v_add_f32_e32 v117, v113, v124
	v_add_f32_e32 v113, v118, v122
	v_add_f32_e32 v118, v114, v126
	v_add_f32_e32 v114, v119, v123
	v_add_f32_e32 v115, v115, v125
	v_cvt_pk_bf16_f32 v112, v116, v112
	v_cvt_pk_bf16_f32 v113, v113, v114
	v_cvt_pk_bf16_f32 v114, v120, v117
	v_cvt_pk_bf16_f32 v115, v118, v115
	global_store_dwordx4 v[162:163], v[112:115], off offset:256
	global_load_dwordx4 v[112:115], v[160:161], off
	v_lshl_add_u64 v[124:125], v[158:159], 2, s[4:5]
	global_load_dwordx4 v[116:119], v[124:125], off nt
	global_load_dwordx4 v[120:123], v[124:125], off offset:16 nt
	s_waitcnt vmcnt(0)
	v_lshlrev_b32_e32 v126, 16, v112
	v_and_b32_e32 v112, 0xffff0000, v112
	v_lshlrev_b32_e32 v127, 16, v113
	v_and_b32_e32 v113, 0xffff0000, v113
	v_lshlrev_b32_e32 v153, 16, v114
	v_and_b32_e32 v114, 0xffff0000, v114
	v_lshlrev_b32_e32 v154, 16, v115
	v_and_b32_e32 v115, 0xffff0000, v115
	v_add_f32_e32 v116, v116, v126
	v_add_f32_e32 v120, v120, v153
	v_add_f32_e32 v112, v117, v112
	v_add_f32_e32 v114, v121, v114
	v_add_f32_e32 v117, v118, v127
	v_add_f32_e32 v118, v122, v154
	v_add_f32_e32 v113, v119, v113
	v_add_f32_e32 v115, v123, v115
	v_add_f32_e32 v108, v108, v116
	v_add_f32_e32 v116, v104, v120
	v_add_f32_e32 v104, v109, v112
	v_add_f32_e32 v109, v105, v114
	v_add_f32_e32 v105, v110, v117
	v_add_f32_e32 v110, v106, v118
	v_add_f32_e32 v106, v111, v113
	v_add_f32_e32 v107, v107, v115
	v_cvt_pk_bf16_f32 v104, v108, v104
	v_cvt_pk_bf16_f32 v105, v105, v106
	v_cvt_pk_bf16_f32 v106, v116, v109
	v_cvt_pk_bf16_f32 v107, v110, v107
	global_load_dwordx4 v[108:111], v[160:161], off offset:256
	v_lshl_add_u64 v[116:117], v[146:147], 0, s[24:25]
	global_store_dwordx4 v[160:161], v[104:107], off
	global_load_dwordx4 v[104:107], v[124:125], off offset:512 nt
	s_nop 0
	global_load_dwordx4 v[112:115], v[124:125], off offset:528 nt
	v_lshl_add_u64 v[118:119], v[116:117], 1, s[30:31]
	s_waitcnt vmcnt(0)
	v_lshlrev_b32_e32 v120, 16, v108
	v_and_b32_e32 v108, 0xffff0000, v108
	v_lshlrev_b32_e32 v121, 16, v109
	v_and_b32_e32 v109, 0xffff0000, v109
	v_lshlrev_b32_e32 v122, 16, v110
	v_and_b32_e32 v110, 0xffff0000, v110
	v_lshlrev_b32_e32 v123, 16, v111
	v_and_b32_e32 v111, 0xffff0000, v111
	v_add_f32_e32 v104, v104, v120
	v_add_f32_e32 v112, v112, v122
	v_add_f32_e32 v105, v105, v108
	v_add_f32_e32 v108, v113, v110
	v_add_f32_e32 v106, v106, v121
	v_add_f32_e32 v110, v114, v123
	v_add_f32_e32 v107, v107, v109
	v_add_f32_e32 v109, v115, v111
	v_add_f32_e32 v100, v100, v104
	v_add_f32_e32 v104, v96, v112
	v_add_f32_e32 v96, v101, v105
	v_add_f32_e32 v101, v97, v108
	v_add_f32_e32 v97, v102, v106
	v_add_f32_e32 v102, v98, v110
	v_add_f32_e32 v98, v103, v107
	v_add_f32_e32 v99, v99, v109
	v_cvt_pk_bf16_f32 v96, v100, v96
	v_cvt_pk_bf16_f32 v97, v97, v98
	v_cvt_pk_bf16_f32 v98, v104, v101
	v_cvt_pk_bf16_f32 v99, v102, v99
	global_store_dwordx4 v[160:161], v[96:99], off offset:256
	global_load_dwordx4 v[96:99], v[118:119], off
	v_lshl_add_u64 v[108:109], v[116:117], 2, s[4:5]
	global_load_dwordx4 v[100:103], v[108:109], off nt
	global_load_dwordx4 v[104:107], v[108:109], off offset:16 nt
	s_waitcnt vmcnt(0)
	v_lshlrev_b32_e32 v110, 16, v96
	v_and_b32_e32 v96, 0xffff0000, v96
	v_lshlrev_b32_e32 v111, 16, v97
	v_and_b32_e32 v97, 0xffff0000, v97
	v_lshlrev_b32_e32 v112, 16, v98
	v_and_b32_e32 v98, 0xffff0000, v98
	v_lshlrev_b32_e32 v113, 16, v99
	v_and_b32_e32 v99, 0xffff0000, v99
	v_add_f32_e32 v100, v100, v110
	v_add_f32_e32 v104, v104, v112
	v_add_f32_e32 v96, v101, v96
	v_add_f32_e32 v98, v105, v98
	v_add_f32_e32 v101, v102, v111
	v_add_f32_e32 v102, v106, v113
	v_add_f32_e32 v97, v103, v97
	v_add_f32_e32 v99, v107, v99
	v_add_f32_e32 v92, v92, v100
	v_add_f32_e32 v100, v88, v104
	v_add_f32_e32 v88, v93, v96
	v_add_f32_e32 v93, v89, v98
	v_add_f32_e32 v89, v94, v101
	v_add_f32_e32 v94, v90, v102
	v_add_f32_e32 v90, v95, v97
	v_add_f32_e32 v91, v91, v99
	v_cvt_pk_bf16_f32 v88, v92, v88
	v_cvt_pk_bf16_f32 v89, v89, v90
	v_cvt_pk_bf16_f32 v90, v100, v93
	v_cvt_pk_bf16_f32 v91, v94, v91
	global_load_dwordx4 v[92:95], v[118:119], off offset:256
	v_lshl_add_u64 v[100:101], v[146:147], 0, s[26:27]
	global_store_dwordx4 v[118:119], v[88:91], off
	global_load_dwordx4 v[88:91], v[108:109], off offset:512 nt
	s_nop 0
	global_load_dwordx4 v[96:99], v[108:109], off offset:528 nt
	v_lshl_add_u64 v[102:103], v[100:101], 1, s[30:31]
	s_waitcnt vmcnt(0)
	v_lshlrev_b32_e32 v104, 16, v92
	v_and_b32_e32 v92, 0xffff0000, v92
	v_lshlrev_b32_e32 v105, 16, v93
	v_and_b32_e32 v93, 0xffff0000, v93
	v_lshlrev_b32_e32 v106, 16, v94
	v_and_b32_e32 v94, 0xffff0000, v94
	v_lshlrev_b32_e32 v107, 16, v95
	v_and_b32_e32 v95, 0xffff0000, v95
	v_add_f32_e32 v88, v88, v104
	v_add_f32_e32 v96, v96, v106
	v_add_f32_e32 v89, v89, v92
	v_add_f32_e32 v92, v97, v94
	v_add_f32_e32 v90, v90, v105
	v_add_f32_e32 v94, v98, v107
	v_add_f32_e32 v91, v91, v93
	v_add_f32_e32 v93, v99, v95
	v_add_f32_e32 v84, v84, v88
	v_add_f32_e32 v88, v80, v96
	v_add_f32_e32 v80, v85, v89
	v_add_f32_e32 v85, v81, v92
	v_add_f32_e32 v81, v86, v90
	v_add_f32_e32 v86, v82, v94
	v_add_f32_e32 v82, v87, v91
	v_add_f32_e32 v83, v83, v93
	v_cvt_pk_bf16_f32 v80, v84, v80
	v_cvt_pk_bf16_f32 v81, v81, v82
	v_cvt_pk_bf16_f32 v82, v88, v85
	v_cvt_pk_bf16_f32 v83, v86, v83
	global_store_dwordx4 v[118:119], v[80:83], off offset:256
	global_load_dwordx4 v[80:83], v[102:103], off
	v_lshl_add_u64 v[92:93], v[100:101], 2, s[4:5]
	global_load_dwordx4 v[84:87], v[92:93], off nt
	global_load_dwordx4 v[88:91], v[92:93], off offset:16 nt
	s_waitcnt vmcnt(0)
; __device__ __forceinline__ unsigned pkbf(float lo, float hi) { return pg8::cvt_pk_bf16(lo, hi); }
; __device__ __forceinline__ void unpack8bf(const u32x4 w, float* f) { f[0] = bflo(w.x); f[1] = bfhi(w.x); f[2] = bflo(w.y); f[3] = bfhi(w.y); f[4] = bflo(w.z); f[5] = bfhi(w.z); f[6] = bflo(w.w); f[7] = bfhi(w.w); }
;     __device__ __forceinline__ void operator()(AccRef acc, const Unit& u, int wr, int wc, int fr, int fq) const {
;     ...
;                     const size_t off = (size_t)(row0 + ai * 128 + m * 16) * DM + col0 + bj * 128;
;                     const f32x4 x0 = *(const f32x4*)(xb + off), x1 = *(const f32x4*)(xb + off + 4);
;                     const u32x4 dw = *(const u32x4*)(D1 + off); float d[8]; unpack8bf(dw, d);
;                     float o[8];
; #pragma unroll
;                     for (int e = 0; e < 4; ++e) { o[e] = x0[e] + d[e] + acc[ai][bj][m][0][e]; o[4 + e] = x1[e] + d[4 + e] + acc[ai][bj][m][1][e]; }
;                     u32x4 w; w.x = pkbf(o[0], o[1]); w.y = pkbf(o[2], o[3]); w.z = pkbf(o[4], o[5]); w.w = pkbf(o[6], o[7]);
;                     *(u32x4*)(D1 + off) = w;
	v_lshlrev_b32_e32 v94, 16, v80
	v_and_b32_e32 v80, 0xffff0000, v80
	v_lshlrev_b32_e32 v95, 16, v81
	v_and_b32_e32 v81, 0xffff0000, v81
	v_lshlrev_b32_e32 v96, 16, v82
	v_and_b32_e32 v82, 0xffff0000, v82
	v_lshlrev_b32_e32 v97, 16, v83
	v_and_b32_e32 v83, 0xffff0000, v83
	v_add_f32_e32 v84, v84, v94
	v_add_f32_e32 v88, v88, v96
	v_add_f32_e32 v80, v85, v80
	v_add_f32_e32 v82, v89, v82
	v_add_f32_e32 v85, v86, v95
	v_add_f32_e32 v86, v90, v97
	v_add_f32_e32 v81, v87, v81
	v_add_f32_e32 v83, v91, v83
	v_add_f32_e32 v76, v76, v84
	v_add_f32_e32 v84, v72, v88
	v_add_f32_e32 v72, v77, v80
	v_add_f32_e32 v77, v73, v82
	v_add_f32_e32 v73, v78, v85
	v_add_f32_e32 v78, v74, v86
	v_add_f32_e32 v74, v79, v81
	v_add_f32_e32 v75, v75, v83
	v_cvt_pk_bf16_f32 v72, v76, v72
	v_cvt_pk_bf16_f32 v73, v73, v74
	v_cvt_pk_bf16_f32 v74, v84, v77
	v_cvt_pk_bf16_f32 v75, v78, v75
	global_load_dwordx4 v[76:79], v[102:103], off offset:256
	v_lshl_add_u64 v[84:85], v[146:147], 0, s[28:29]
	global_store_dwordx4 v[102:103], v[72:75], off
	global_load_dwordx4 v[72:75], v[92:93], off offset:512 nt
	s_nop 0
	global_load_dwordx4 v[80:83], v[92:93], off offset:528 nt
	v_lshl_add_u64 v[86:87], v[84:85], 1, s[30:31]
	s_waitcnt vmcnt(0)
	v_lshlrev_b32_e32 v88, 16, v76
	v_and_b32_e32 v76, 0xffff0000, v76
	v_lshlrev_b32_e32 v89, 16, v77
	v_and_b32_e32 v77, 0xffff0000, v77
	v_lshlrev_b32_e32 v90, 16, v78
	v_and_b32_e32 v78, 0xffff0000, v78
	v_lshlrev_b32_e32 v91, 16, v79
	v_and_b32_e32 v79, 0xffff0000, v79
	v_add_f32_e32 v72, v72, v88
	v_add_f32_e32 v80, v80, v90
	v_add_f32_e32 v73, v73, v76
	v_add_f32_e32 v76, v81, v78
	v_add_f32_e32 v74, v74, v89
	v_add_f32_e32 v78, v82, v91
	v_add_f32_e32 v75, v75, v77
	v_add_f32_e32 v77, v83, v79
	v_add_f32_e32 v68, v68, v72
	v_add_f32_e32 v72, v64, v80
	v_add_f32_e32 v64, v69, v73
	v_add_f32_e32 v69, v65, v76
	v_add_f32_e32 v65, v70, v74
	v_add_f32_e32 v70, v66, v78
	v_add_f32_e32 v66, v71, v75
	v_add_f32_e32 v67, v67, v77
	v_cvt_pk_bf16_f32 v64, v68, v64
	v_cvt_pk_bf16_f32 v65, v65, v66
	v_cvt_pk_bf16_f32 v66, v72, v69
	v_cvt_pk_bf16_f32 v67, v70, v67
	global_store_dwordx4 v[102:103], v[64:67], off offset:256
	global_load_dwordx4 v[64:67], v[86:87], off
	v_lshl_add_u64 v[76:77], v[84:85], 2, s[4:5]
	global_load_dwordx4 v[68:71], v[76:77], off nt
	global_load_dwordx4 v[72:75], v[76:77], off offset:16 nt
	s_waitcnt vmcnt(0)
	v_lshlrev_b32_e32 v78, 16, v64
	v_and_b32_e32 v64, 0xffff0000, v64
	v_lshlrev_b32_e32 v79, 16, v65
	v_and_b32_e32 v65, 0xffff0000, v65
	v_lshlrev_b32_e32 v80, 16, v66
	v_and_b32_e32 v66, 0xffff0000, v66
	v_lshlrev_b32_e32 v81, 16, v67
	v_and_b32_e32 v67, 0xffff0000, v67
	v_add_f32_e32 v68, v68, v78
	v_add_f32_e32 v72, v72, v80
	v_add_f32_e32 v64, v69, v64
	v_add_f32_e32 v66, v73, v66
	v_add_f32_e32 v69, v70, v79
	v_add_f32_e32 v70, v74, v81
	v_add_f32_e32 v65, v71, v65
	v_add_f32_e32 v67, v75, v67
	v_add_f32_e32 v60, v60, v68
	v_add_f32_e32 v68, v56, v72
	v_add_f32_e32 v56, v61, v64
	v_add_f32_e32 v61, v57, v66
	v_add_f32_e32 v57, v62, v69
	v_add_f32_e32 v62, v58, v70
	v_add_f32_e32 v58, v63, v65
	v_add_f32_e32 v59, v59, v67
	v_cvt_pk_bf16_f32 v56, v60, v56
	v_cvt_pk_bf16_f32 v57, v57, v58
	v_cvt_pk_bf16_f32 v58, v68, v61
	v_cvt_pk_bf16_f32 v59, v62, v59
	global_load_dwordx4 v[60:63], v[86:87], off offset:256
	v_lshl_add_u64 v[68:69], v[146:147], 0, s[36:37]
	global_store_dwordx4 v[86:87], v[56:59], off
	global_load_dwordx4 v[56:59], v[76:77], off offset:512 nt
	s_nop 0
	global_load_dwordx4 v[64:67], v[76:77], off offset:528 nt
	v_lshl_add_u64 v[70:71], v[68:69], 1, s[30:31]
	s_waitcnt vmcnt(0)
	v_lshlrev_b32_e32 v72, 16, v60
	v_and_b32_e32 v60, 0xffff0000, v60
	v_lshlrev_b32_e32 v73, 16, v61
	v_and_b32_e32 v61, 0xffff0000, v61
	v_lshlrev_b32_e32 v74, 16, v62
	v_and_b32_e32 v62, 0xffff0000, v62
	v_lshlrev_b32_e32 v75, 16, v63
	v_and_b32_e32 v63, 0xffff0000, v63
	v_add_f32_e32 v56, v56, v72
	v_add_f32_e32 v64, v64, v74
	v_add_f32_e32 v57, v57, v60
	v_add_f32_e32 v60, v65, v62
	v_add_f32_e32 v58, v58, v73
	v_add_f32_e32 v62, v66, v75
	v_add_f32_e32 v59, v59, v61
	v_add_f32_e32 v61, v67, v63
	v_add_f32_e32 v52, v52, v56
	v_add_f32_e32 v56, v48, v64
	v_add_f32_e32 v48, v53, v57
	v_add_f32_e32 v53, v49, v60
	v_add_f32_e32 v49, v54, v58
	v_add_f32_e32 v54, v50, v62
	v_add_f32_e32 v50, v55, v59
	v_add_f32_e32 v51, v51, v61
	v_cvt_pk_bf16_f32 v48, v52, v48
	v_cvt_pk_bf16_f32 v49, v49, v50
	v_cvt_pk_bf16_f32 v50, v56, v53
	v_cvt_pk_bf16_f32 v51, v54, v51
	global_store_dwordx4 v[86:87], v[48:51], off offset:256
	global_load_dwordx4 v[48:51], v[70:71], off
	v_lshl_add_u64 v[60:61], v[68:69], 2, s[4:5]
	global_load_dwordx4 v[52:55], v[60:61], off nt
	global_load_dwordx4 v[56:59], v[60:61], off offset:16 nt
	s_waitcnt vmcnt(0)
	v_lshlrev_b32_e32 v62, 16, v48
	v_and_b32_e32 v48, 0xffff0000, v48
	v_lshlrev_b32_e32 v63, 16, v49
	v_and_b32_e32 v49, 0xffff0000, v49
	v_lshlrev_b32_e32 v64, 16, v50
	v_and_b32_e32 v50, 0xffff0000, v50
	v_lshlrev_b32_e32 v65, 16, v51
	v_and_b32_e32 v51, 0xffff0000, v51
	v_add_f32_e32 v52, v52, v62
	v_add_f32_e32 v56, v56, v64
	v_add_f32_e32 v48, v53, v48
	v_add_f32_e32 v50, v57, v50
	v_add_f32_e32 v53, v54, v63
	v_add_f32_e32 v54, v58, v65
	v_add_f32_e32 v49, v55, v49
	v_add_f32_e32 v51, v59, v51
	v_add_f32_e32 v44, v44, v52
	v_add_f32_e32 v52, v40, v56
	v_add_f32_e32 v40, v45, v48
	v_add_f32_e32 v45, v41, v50
	v_add_f32_e32 v41, v46, v53
	v_add_f32_e32 v46, v42, v54
	v_add_f32_e32 v42, v47, v49
	v_add_f32_e32 v43, v43, v51
	v_cvt_pk_bf16_f32 v40, v44, v40
	v_cvt_pk_bf16_f32 v41, v41, v42
	v_cvt_pk_bf16_f32 v42, v52, v45
	v_cvt_pk_bf16_f32 v43, v46, v43
	global_load_dwordx4 v[44:47], v[70:71], off offset:256
	v_lshl_add_u64 v[52:53], v[146:147], 0, s[40:41]
	global_store_dwordx4 v[70:71], v[40:43], off
	global_load_dwordx4 v[40:43], v[60:61], off offset:512 nt
	s_nop 0
	global_load_dwordx4 v[48:51], v[60:61], off offset:528 nt
	v_lshl_add_u64 v[54:55], v[52:53], 1, s[30:31]
	s_waitcnt vmcnt(0)
; __device__ __forceinline__ unsigned pkbf(float lo, float hi) { return pg8::cvt_pk_bf16(lo, hi); }
; __device__ __forceinline__ void unpack8bf(const u32x4 w, float* f) { f[0] = bflo(w.x); f[1] = bfhi(w.x); f[2] = bflo(w.y); f[3] = bfhi(w.y); f[4] = bflo(w.z); f[5] = bfhi(w.z); f[6] = bflo(w.w); f[7] = bfhi(w.w); }
;     __device__ __forceinline__ void operator()(AccRef acc, const Unit& u, int wr, int wc, int fr, int fq) const {
;     ...
;                     const size_t off = (size_t)(row0 + ai * 128 + m * 16) * DM + col0 + bj * 128;
;                     const f32x4 x0 = *(const f32x4*)(xb + off), x1 = *(const f32x4*)(xb + off + 4);
;                     const u32x4 dw = *(const u32x4*)(D1 + off); float d[8]; unpack8bf(dw, d);
;                     float o[8];
; #pragma unroll
;                     for (int e = 0; e < 4; ++e) { o[e] = x0[e] + d[e] + acc[ai][bj][m][0][e]; o[4 + e] = x1[e] + d[4 + e] + acc[ai][bj][m][1][e]; }
;                     u32x4 w; w.x = pkbf(o[0], o[1]); w.y = pkbf(o[2], o[3]); w.z = pkbf(o[4], o[5]); w.w = pkbf(o[6], o[7]);
;                     *(u32x4*)(D1 + off) = w;
	v_lshlrev_b32_e32 v56, 16, v44
	v_and_b32_e32 v44, 0xffff0000, v44
	v_lshlrev_b32_e32 v57, 16, v45
	v_and_b32_e32 v45, 0xffff0000, v45
	v_lshlrev_b32_e32 v58, 16, v46
	v_and_b32_e32 v46, 0xffff0000, v46
	v_lshlrev_b32_e32 v59, 16, v47
	v_and_b32_e32 v47, 0xffff0000, v47
	v_add_f32_e32 v40, v40, v56
	v_add_f32_e32 v48, v48, v58
	v_add_f32_e32 v41, v41, v44
	v_add_f32_e32 v44, v49, v46
	v_add_f32_e32 v42, v42, v57
	v_add_f32_e32 v46, v50, v59
	v_add_f32_e32 v43, v43, v45
	v_add_f32_e32 v45, v51, v47
	v_add_f32_e32 v36, v36, v40
	v_add_f32_e32 v40, v32, v48
	v_add_f32_e32 v32, v37, v41
	v_add_f32_e32 v37, v33, v44
	v_add_f32_e32 v33, v38, v42
	v_add_f32_e32 v38, v34, v46
	v_add_f32_e32 v34, v39, v43
	v_add_f32_e32 v35, v35, v45
	v_cvt_pk_bf16_f32 v32, v36, v32
	v_cvt_pk_bf16_f32 v33, v33, v34
	v_cvt_pk_bf16_f32 v34, v40, v37
	v_cvt_pk_bf16_f32 v35, v38, v35
	global_store_dwordx4 v[70:71], v[32:35], off offset:256
	global_load_dwordx4 v[32:35], v[54:55], off
	v_lshl_add_u64 v[44:45], v[52:53], 2, s[4:5]
	global_load_dwordx4 v[36:39], v[44:45], off nt
	global_load_dwordx4 v[40:43], v[44:45], off offset:16 nt
	s_waitcnt vmcnt(0)
	v_lshlrev_b32_e32 v46, 16, v32
	v_and_b32_e32 v32, 0xffff0000, v32
	v_lshlrev_b32_e32 v47, 16, v33
	v_and_b32_e32 v33, 0xffff0000, v33
	v_lshlrev_b32_e32 v48, 16, v34
	v_and_b32_e32 v34, 0xffff0000, v34
	v_lshlrev_b32_e32 v49, 16, v35
	v_and_b32_e32 v35, 0xffff0000, v35
	v_add_f32_e32 v36, v36, v46
	v_add_f32_e32 v40, v40, v48
	v_add_f32_e32 v32, v37, v32
	v_add_f32_e32 v34, v41, v34
	v_add_f32_e32 v37, v38, v47
	v_add_f32_e32 v38, v42, v49
	v_add_f32_e32 v33, v39, v33
	v_add_f32_e32 v35, v43, v35
	v_add_f32_e32 v28, v28, v36
	v_add_f32_e32 v36, v24, v40
	v_add_f32_e32 v24, v29, v32
	v_add_f32_e32 v29, v25, v34
	v_add_f32_e32 v25, v30, v37
	v_add_f32_e32 v30, v26, v38
	v_add_f32_e32 v26, v31, v33
	v_add_f32_e32 v27, v27, v35
	v_cvt_pk_bf16_f32 v24, v28, v24
	v_cvt_pk_bf16_f32 v25, v25, v26
	v_cvt_pk_bf16_f32 v26, v36, v29
	v_cvt_pk_bf16_f32 v27, v30, v27
	global_load_dwordx4 v[28:31], v[54:55], off offset:256
	v_lshl_add_u64 v[36:37], v[146:147], 0, s[42:43]
	global_store_dwordx4 v[54:55], v[24:27], off
	global_load_dwordx4 v[24:27], v[44:45], off offset:512 nt
	s_nop 0
	global_load_dwordx4 v[32:35], v[44:45], off offset:528 nt
	v_lshl_add_u64 v[38:39], v[36:37], 1, s[30:31]
	s_waitcnt vmcnt(0)
	v_lshlrev_b32_e32 v40, 16, v28
	v_and_b32_e32 v28, 0xffff0000, v28
	v_lshlrev_b32_e32 v41, 16, v29
	v_and_b32_e32 v29, 0xffff0000, v29
	v_lshlrev_b32_e32 v42, 16, v30
	v_and_b32_e32 v30, 0xffff0000, v30
	v_lshlrev_b32_e32 v43, 16, v31
	v_and_b32_e32 v31, 0xffff0000, v31
	v_add_f32_e32 v24, v24, v40
	v_add_f32_e32 v32, v32, v42
	v_add_f32_e32 v25, v25, v28
	v_add_f32_e32 v28, v33, v30
	v_add_f32_e32 v26, v26, v41
	v_add_f32_e32 v30, v34, v43
	v_add_f32_e32 v27, v27, v29
	v_add_f32_e32 v29, v35, v31
	v_add_f32_e32 v20, v20, v24
	v_add_f32_e32 v24, v16, v32
	v_add_f32_e32 v16, v21, v25
	v_add_f32_e32 v21, v17, v28
	v_add_f32_e32 v17, v22, v26
	v_add_f32_e32 v22, v18, v30
	v_add_f32_e32 v18, v23, v27
	v_add_f32_e32 v19, v19, v29
	v_cvt_pk_bf16_f32 v16, v20, v16
	v_cvt_pk_bf16_f32 v17, v17, v18
	v_cvt_pk_bf16_f32 v18, v24, v21
	v_cvt_pk_bf16_f32 v19, v22, v19
	global_store_dwordx4 v[54:55], v[16:19], off offset:256
	global_load_dwordx4 v[16:19], v[38:39], off
	v_lshl_add_u64 v[28:29], v[36:37], 2, s[4:5]
	global_load_dwordx4 v[20:23], v[28:29], off nt
	global_load_dwordx4 v[24:27], v[28:29], off offset:16 nt
	s_mov_b64 s[4:5], -1
	s_waitcnt vmcnt(0)
	v_lshlrev_b32_e32 v30, 16, v16
	v_and_b32_e32 v16, 0xffff0000, v16
	v_lshlrev_b32_e32 v31, 16, v17
	v_and_b32_e32 v17, 0xffff0000, v17
	v_lshlrev_b32_e32 v32, 16, v18
	v_and_b32_e32 v18, 0xffff0000, v18
	v_lshlrev_b32_e32 v33, 16, v19
	v_and_b32_e32 v19, 0xffff0000, v19
	v_add_f32_e32 v20, v20, v30
	v_add_f32_e32 v24, v24, v32
	v_add_f32_e32 v16, v21, v16
	v_add_f32_e32 v18, v25, v18
	v_add_f32_e32 v21, v22, v31
	v_add_f32_e32 v22, v26, v33
	v_add_f32_e32 v17, v23, v17
	v_add_f32_e32 v19, v27, v19
	v_add_f32_e32 v12, v12, v20
	v_add_f32_e32 v20, v8, v24
	v_add_f32_e32 v8, v13, v16
	v_add_f32_e32 v13, v9, v18
	v_add_f32_e32 v9, v14, v21
	v_add_f32_e32 v14, v10, v22
	v_add_f32_e32 v10, v15, v17
	v_add_f32_e32 v11, v11, v19
	v_cvt_pk_bf16_f32 v8, v12, v8
	v_cvt_pk_bf16_f32 v9, v9, v10
	v_cvt_pk_bf16_f32 v10, v20, v13
	v_cvt_pk_bf16_f32 v11, v14, v11
	global_load_dwordx4 v[12:15], v[38:39], off offset:256
	s_waitcnt vmcnt(0)
	v_lshlrev_b32_e32 v20, 16, v12
	global_store_dwordx4 v[38:39], v[8:11], off
	global_load_dwordx4 v[8:11], v[28:29], off offset:512 nt
	s_nop 0
	global_load_dwordx4 v[16:19], v[28:29], off offset:528 nt
	v_and_b32_e32 v12, 0xffff0000, v12
	v_lshlrev_b32_e32 v21, 16, v13
	v_and_b32_e32 v13, 0xffff0000, v13
	v_lshlrev_b32_e32 v22, 16, v14
	v_and_b32_e32 v14, 0xffff0000, v14
	v_lshlrev_b32_e32 v23, 16, v15
	v_and_b32_e32 v15, 0xffff0000, v15
	s_waitcnt vmcnt(0)
	v_add_f32_e32 v8, v8, v20
	v_add_f32_e32 v16, v16, v22
	v_add_f32_e32 v9, v9, v12
	v_add_f32_e32 v12, v17, v14
	v_add_f32_e32 v10, v10, v21
	v_add_f32_e32 v14, v18, v23
	v_add_f32_e32 v11, v11, v13
	v_add_f32_e32 v13, v19, v15
	v_add_f32_e32 v4, v4, v8
	v_add_f32_e32 v8, v0, v16
	v_add_f32_e32 v0, v5, v9
	v_add_f32_e32 v5, v1, v12
	v_add_f32_e32 v1, v6, v10
	v_add_f32_e32 v6, v2, v14
	v_add_f32_e32 v2, v7, v11
	v_add_f32_e32 v3, v3, v13
	v_cvt_pk_bf16_f32 v0, v4, v0
	v_cvt_pk_bf16_f32 v1, v1, v2
	v_cvt_pk_bf16_f32 v2, v8, v5
	v_cvt_pk_bf16_f32 v3, v6, v3
	global_store_dwordx4 v[38:39], v[0:3], off offset:256
	s_cbranch_vccnz .LBB0_1234
	s_andn2_b64 vcc, exec, s[94:95]
	s_cbranch_vccnz .LBB0_1233
	s_barrier
	s_branch .LBB0_1233

; __device__ __forceinline__ unsigned pkbf(float lo, float hi) { return pg8::cvt_pk_bf16(lo, hi); }
; __device__ __forceinline__ void unpack8bf(const u32x4 w, float* f) { f[0] = bflo(w.x); f[1] = bfhi(w.x); f[2] = bflo(w.y); f[3] = bfhi(w.y); f[4] = bflo(w.z); f[5] = bfhi(w.z); f[6] = bflo(w.w); f[7] = bfhi(w.w); }
;     __device__ __forceinline__ void operator()(AccRef acc, const Unit& u, int wr, int wc, int fr, int fq) const {
;         asm volatile("" : "+v"(fr), "+v"(fq));
;         const int row0 = u.pm * 256 + wr * 64 + fr, col0 = u.pn * 256 + wc * 32 + 8 * fq;
; #pragma unroll
;         for (int ai = 0; ai < 2; ++ai)
; #pragma unroll
;             for (int m = 0; m < 4; ++m)
; #pragma unroll
;                 for (int bj = 0; bj < 2; ++bj) {
;                     const size_t off = (size_t)(row0 + ai * 128 + m * 16) * DM + col0 + bj * 128;
;                     const u32x4 hw = *(const u32x4*)(Hb + off); float h[8]; unpack8bf(hw, h);
; #pragma unroll
;                     for (int e = 0; e < 4; ++e) { h[e] += 0.5f * acc[ai][bj][m][0][e]; h[4 + e] += 0.5f * acc[ai][bj][m][1][e]; }
;                     u32x4 w; w.x = pkbf(h[0], h[1]); w.y = pkbf(h[2], h[3]); w.z = pkbf(h[4], h[5]); w.w = pkbf(h[6], h[7]);
;                     *(u32x4*)(Hb + off) = w;
;                 }
;     }
.LBB0_1443:
	v_mov_b32_e32 v146, v129
	v_mov_b32_e32 v147, v148
	s_lshl_b32 s14, s77, 8
	s_add_i32 s14, s14, s64
	v_add_u32_e32 v146, s14, v146
	s_lshl_b32 s14, s78, 8
	s_or_b32 s14, s14, s65
	v_lshl_add_u32 v154, v147, 3, s14
	v_ashrrev_i32_e32 v147, 31, v146
	v_lshlrev_b64 v[146:147], 11, v[146:147]
	v_ashrrev_i32_e32 v155, 31, v154
	v_lshl_add_u64 v[146:147], s[30:31], 0, v[146:147]
	v_lshl_add_u64 v[146:147], v[154:155], 1, v[146:147]
	global_load_dwordx4 v[154:157], v[146:147], off
	s_mov_b64 s[98:99], 0x8000
	s_mov_b64 s[100:101], 0x28000
	v_mov_b64_e32 v[180:181], v[146:147]
	global_load_dwordx4 v[176:179], v[180:181], off offset:256
	v_lshl_add_u64 v[180:181], v[180:181], 0, s[98:99]
	global_load_dwordx4 v[176:179], v[180:181], off
	global_load_dwordx4 v[176:179], v[180:181], off offset:256
	v_lshl_add_u64 v[180:181], v[180:181], 0, s[98:99]
	global_load_dwordx4 v[176:179], v[180:181], off
	global_load_dwordx4 v[176:179], v[180:181], off offset:256
	v_lshl_add_u64 v[180:181], v[180:181], 0, s[98:99]
	global_load_dwordx4 v[176:179], v[180:181], off
	global_load_dwordx4 v[176:179], v[180:181], off offset:256
	v_lshl_add_u64 v[180:181], v[180:181], 0, s[100:101]
	global_load_dwordx4 v[176:179], v[180:181], off
	global_load_dwordx4 v[176:179], v[180:181], off offset:256
	v_lshl_add_u64 v[180:181], v[180:181], 0, s[98:99]
	global_load_dwordx4 v[176:179], v[180:181], off
	global_load_dwordx4 v[176:179], v[180:181], off offset:256
	v_lshl_add_u64 v[180:181], v[180:181], 0, s[98:99]
	global_load_dwordx4 v[176:179], v[180:181], off
	global_load_dwordx4 v[176:179], v[180:181], off offset:256
	v_lshl_add_u64 v[180:181], v[180:181], 0, s[98:99]
	global_load_dwordx4 v[176:179], v[180:181], off
	global_load_dwordx4 v[176:179], v[180:181], off offset:256
	s_waitcnt vmcnt(0)
	v_lshlrev_b32_e32 v153, 16, v154
	v_and_b32_e32 v154, 0xffff0000, v154
	v_lshlrev_b32_e32 v158, 16, v155
	v_and_b32_e32 v155, 0xffff0000, v155
	v_lshlrev_b32_e32 v159, 16, v156
	v_and_b32_e32 v156, 0xffff0000, v156
	v_lshlrev_b32_e32 v160, 16, v157
	v_and_b32_e32 v157, 0xffff0000, v157
	v_fmac_f32_e32 v153, 0.5, v120
	v_fmac_f32_e32 v159, 0.5, v124
	v_fmac_f32_e32 v154, 0.5, v121
	v_fmac_f32_e32 v156, 0.5, v125
	v_fmac_f32_e32 v158, 0.5, v122
	v_fmac_f32_e32 v160, 0.5, v126
	v_fmac_f32_e32 v155, 0.5, v123
	v_fmac_f32_e32 v157, 0.5, v127
	v_cvt_pk_bf16_f32 v120, v153, v154
	v_cvt_pk_bf16_f32 v121, v158, v155
	v_cvt_pk_bf16_f32 v122, v159, v156
	v_cvt_pk_bf16_f32 v123, v160, v157
	global_load_dwordx4 v[124:127], v[146:147], off offset:256
	v_add_co_u32_e32 v154, vcc, s67, v146
	global_store_dwordx4 v[146:147], v[120:123], off
	s_nop 0
	v_addc_co_u32_e32 v155, vcc, 0, v147, vcc
	s_waitcnt vmcnt(1)
	v_lshlrev_b32_e32 v120, 16, v124
	v_and_b32_e32 v121, 0xffff0000, v124
	v_lshlrev_b32_e32 v122, 16, v125
	v_and_b32_e32 v123, 0xffff0000, v125
	v_lshlrev_b32_e32 v124, 16, v126
	v_and_b32_e32 v125, 0xffff0000, v126
	v_lshlrev_b32_e32 v126, 16, v127
	v_and_b32_e32 v127, 0xffff0000, v127
	v_fmac_f32_e32 v120, 0.5, v116
	v_fmac_f32_e32 v124, 0.5, v112
	v_fmac_f32_e32 v121, 0.5, v117
	v_fmac_f32_e32 v125, 0.5, v113
	v_fmac_f32_e32 v122, 0.5, v118
	v_fmac_f32_e32 v126, 0.5, v114
	v_fmac_f32_e32 v123, 0.5, v119
	v_fmac_f32_e32 v127, 0.5, v115
	v_cvt_pk_bf16_f32 v112, v120, v121
	v_cvt_pk_bf16_f32 v113, v122, v123
	v_cvt_pk_bf16_f32 v114, v124, v125
	v_cvt_pk_bf16_f32 v115, v126, v127
	global_load_dwordx4 v[116:119], v[154:155], off
	v_lshl_add_u64 v[120:121], v[146:147], 0, s[20:21]
	global_store_dwordx4 v[146:147], v[112:115], off offset:256
	s_waitcnt vmcnt(1)
	s_nop 0
	v_lshlrev_b32_e32 v112, 16, v116
	v_and_b32_e32 v113, 0xffff0000, v116
	v_lshlrev_b32_e32 v114, 16, v117
	v_and_b32_e32 v115, 0xffff0000, v117
	v_lshlrev_b32_e32 v116, 16, v118
	v_and_b32_e32 v117, 0xffff0000, v118
	v_lshlrev_b32_e32 v118, 16, v119
	v_and_b32_e32 v119, 0xffff0000, v119
	v_fmac_f32_e32 v112, 0.5, v108
	v_fmac_f32_e32 v116, 0.5, v104
	v_fmac_f32_e32 v113, 0.5, v109
	v_fmac_f32_e32 v117, 0.5, v105
	v_fmac_f32_e32 v114, 0.5, v110
	v_fmac_f32_e32 v118, 0.5, v106
	v_fmac_f32_e32 v115, 0.5, v111
	v_fmac_f32_e32 v119, 0.5, v107
	v_cvt_pk_bf16_f32 v104, v112, v113
	v_cvt_pk_bf16_f32 v105, v114, v115
	v_cvt_pk_bf16_f32 v106, v116, v117
	v_cvt_pk_bf16_f32 v107, v118, v119
	global_load_dwordx4 v[108:111], v[120:121], off offset:256
	v_add_co_u32_e32 v112, vcc, s60, v146
	global_store_dwordx4 v[154:155], v[104:107], off
	s_nop 0
	v_addc_co_u32_e32 v113, vcc, 0, v147, vcc
	s_waitcnt vmcnt(1)
	v_lshlrev_b32_e32 v104, 16, v108
	v_and_b32_e32 v105, 0xffff0000, v108
	v_lshlrev_b32_e32 v106, 16, v109
	v_and_b32_e32 v107, 0xffff0000, v109
	v_lshlrev_b32_e32 v108, 16, v110
	v_and_b32_e32 v109, 0xffff0000, v110
	v_lshlrev_b32_e32 v110, 16, v111
	v_and_b32_e32 v111, 0xffff0000, v111
	v_fmac_f32_e32 v104, 0.5, v100
	v_fmac_f32_e32 v108, 0.5, v96
	v_fmac_f32_e32 v105, 0.5, v101
	v_fmac_f32_e32 v109, 0.5, v97
	v_fmac_f32_e32 v106, 0.5, v102
	v_fmac_f32_e32 v110, 0.5, v98
	v_fmac_f32_e32 v107, 0.5, v103
	v_fmac_f32_e32 v111, 0.5, v99
	v_cvt_pk_bf16_f32 v96, v104, v105
	v_cvt_pk_bf16_f32 v97, v106, v107
	v_cvt_pk_bf16_f32 v98, v108, v109
	v_cvt_pk_bf16_f32 v99, v110, v111
	global_load_dwordx4 v[100:103], v[112:113], off
	v_lshl_add_u64 v[104:105], v[146:147], 0, s[24:25]
	global_store_dwordx4 v[120:121], v[96:99], off offset:256
	s_waitcnt vmcnt(1)
; __device__ __forceinline__ unsigned pkbf(float lo, float hi) { return pg8::cvt_pk_bf16(lo, hi); }
; __device__ __forceinline__ void unpack8bf(const u32x4 w, float* f) { f[0] = bflo(w.x); f[1] = bfhi(w.x); f[2] = bflo(w.y); f[3] = bfhi(w.y); f[4] = bflo(w.z); f[5] = bfhi(w.z); f[6] = bflo(w.w); f[7] = bfhi(w.w); }
;     __device__ __forceinline__ void operator()(AccRef acc, const Unit& u, int wr, int wc, int fr, int fq) const {
;     ...
;                 for (int bj = 0; bj < 2; ++bj) {
;                     const size_t off = (size_t)(row0 + ai * 128 + m * 16) * DM + col0 + bj * 128;
;                     const u32x4 hw = *(const u32x4*)(Hb + off); float h[8]; unpack8bf(hw, h);
; #pragma unroll
;                     for (int e = 0; e < 4; ++e) { h[e] += 0.5f * acc[ai][bj][m][0][e]; h[4 + e] += 0.5f * acc[ai][bj][m][1][e]; }
;                     u32x4 w; w.x = pkbf(h[0], h[1]); w.y = pkbf(h[2], h[3]); w.z = pkbf(h[4], h[5]); w.w = pkbf(h[6], h[7]);
;                     *(u32x4*)(Hb + off) = w;
;                 }
	s_nop 0
	v_lshlrev_b32_e32 v96, 16, v100
	v_and_b32_e32 v97, 0xffff0000, v100
	v_lshlrev_b32_e32 v98, 16, v101
	v_and_b32_e32 v99, 0xffff0000, v101
	v_lshlrev_b32_e32 v100, 16, v102
	v_and_b32_e32 v101, 0xffff0000, v102
	v_lshlrev_b32_e32 v102, 16, v103
	v_and_b32_e32 v103, 0xffff0000, v103
	v_fmac_f32_e32 v96, 0.5, v92
	v_fmac_f32_e32 v100, 0.5, v88
	v_fmac_f32_e32 v97, 0.5, v93
	v_fmac_f32_e32 v101, 0.5, v89
	v_fmac_f32_e32 v98, 0.5, v94
	v_fmac_f32_e32 v102, 0.5, v90
	v_fmac_f32_e32 v99, 0.5, v95
	v_fmac_f32_e32 v103, 0.5, v91
	v_cvt_pk_bf16_f32 v88, v96, v97
	v_cvt_pk_bf16_f32 v89, v98, v99
	v_cvt_pk_bf16_f32 v90, v100, v101
	v_cvt_pk_bf16_f32 v91, v102, v103
	global_load_dwordx4 v[92:95], v[104:105], off offset:256
	v_add_co_u32_e32 v96, vcc, s66, v146
	global_store_dwordx4 v[112:113], v[88:91], off
	s_nop 0
	v_addc_co_u32_e32 v97, vcc, 0, v147, vcc
	s_waitcnt vmcnt(1)
	v_lshlrev_b32_e32 v88, 16, v92
	v_and_b32_e32 v89, 0xffff0000, v92
	v_lshlrev_b32_e32 v90, 16, v93
	v_and_b32_e32 v91, 0xffff0000, v93
	v_lshlrev_b32_e32 v92, 16, v94
	v_and_b32_e32 v93, 0xffff0000, v94
	v_lshlrev_b32_e32 v94, 16, v95
	v_and_b32_e32 v95, 0xffff0000, v95
	v_fmac_f32_e32 v88, 0.5, v84
	v_fmac_f32_e32 v92, 0.5, v80
	v_fmac_f32_e32 v89, 0.5, v85
	v_fmac_f32_e32 v93, 0.5, v81
	v_fmac_f32_e32 v90, 0.5, v86
	v_fmac_f32_e32 v94, 0.5, v82
	v_fmac_f32_e32 v91, 0.5, v87
	v_fmac_f32_e32 v95, 0.5, v83
	v_cvt_pk_bf16_f32 v80, v88, v89
	v_cvt_pk_bf16_f32 v81, v90, v91
	v_cvt_pk_bf16_f32 v82, v92, v93
	v_cvt_pk_bf16_f32 v83, v94, v95
	global_load_dwordx4 v[84:87], v[96:97], off
	v_lshl_add_u64 v[88:89], v[146:147], 0, s[26:27]
	global_store_dwordx4 v[104:105], v[80:83], off offset:256
	s_waitcnt vmcnt(1)
	s_nop 0
	v_lshlrev_b32_e32 v80, 16, v84
	v_and_b32_e32 v81, 0xffff0000, v84
	v_lshlrev_b32_e32 v82, 16, v85
	v_and_b32_e32 v83, 0xffff0000, v85
	v_lshlrev_b32_e32 v84, 16, v86
	v_and_b32_e32 v85, 0xffff0000, v86
	v_lshlrev_b32_e32 v86, 16, v87
	v_and_b32_e32 v87, 0xffff0000, v87
	v_fmac_f32_e32 v80, 0.5, v76
	v_fmac_f32_e32 v84, 0.5, v72
	v_fmac_f32_e32 v81, 0.5, v77
	v_fmac_f32_e32 v85, 0.5, v73
	v_fmac_f32_e32 v82, 0.5, v78
	v_fmac_f32_e32 v86, 0.5, v74
	v_fmac_f32_e32 v83, 0.5, v79
	v_fmac_f32_e32 v87, 0.5, v75
	v_cvt_pk_bf16_f32 v72, v80, v81
	v_cvt_pk_bf16_f32 v73, v82, v83
	v_cvt_pk_bf16_f32 v74, v84, v85
	v_cvt_pk_bf16_f32 v75, v86, v87
	global_load_dwordx4 v[76:79], v[88:89], off offset:256
	v_add_co_u32_e32 v80, vcc, s71, v146
	global_store_dwordx4 v[96:97], v[72:75], off
	s_nop 0
	v_addc_co_u32_e32 v81, vcc, 0, v147, vcc
	s_waitcnt vmcnt(1)
	v_lshlrev_b32_e32 v72, 16, v76
	v_and_b32_e32 v73, 0xffff0000, v76
	v_lshlrev_b32_e32 v74, 16, v77
	v_and_b32_e32 v75, 0xffff0000, v77
	v_lshlrev_b32_e32 v76, 16, v78
	v_and_b32_e32 v77, 0xffff0000, v78
	v_lshlrev_b32_e32 v78, 16, v79
	v_and_b32_e32 v79, 0xffff0000, v79
	v_fmac_f32_e32 v72, 0.5, v68
	v_fmac_f32_e32 v76, 0.5, v64
	v_fmac_f32_e32 v73, 0.5, v69
	v_fmac_f32_e32 v77, 0.5, v65
	v_fmac_f32_e32 v74, 0.5, v70
	v_fmac_f32_e32 v78, 0.5, v66
	v_fmac_f32_e32 v75, 0.5, v71
	v_fmac_f32_e32 v79, 0.5, v67
	v_cvt_pk_bf16_f32 v64, v72, v73
	v_cvt_pk_bf16_f32 v65, v74, v75
	v_cvt_pk_bf16_f32 v66, v76, v77
	v_cvt_pk_bf16_f32 v67, v78, v79
	global_load_dwordx4 v[68:71], v[80:81], off
	v_lshl_add_u64 v[72:73], v[146:147], 0, s[28:29]
	global_store_dwordx4 v[88:89], v[64:67], off offset:256
	s_waitcnt vmcnt(1)
	s_nop 0
	v_lshlrev_b32_e32 v64, 16, v68
	v_and_b32_e32 v65, 0xffff0000, v68
	v_lshlrev_b32_e32 v66, 16, v69
	v_and_b32_e32 v67, 0xffff0000, v69
	v_lshlrev_b32_e32 v68, 16, v70
	v_and_b32_e32 v69, 0xffff0000, v70
	v_lshlrev_b32_e32 v70, 16, v71
	v_and_b32_e32 v71, 0xffff0000, v71
	v_fmac_f32_e32 v64, 0.5, v60
	v_fmac_f32_e32 v68, 0.5, v56
	v_fmac_f32_e32 v65, 0.5, v61
	v_fmac_f32_e32 v69, 0.5, v57
	v_fmac_f32_e32 v66, 0.5, v62
	v_fmac_f32_e32 v70, 0.5, v58
	v_fmac_f32_e32 v67, 0.5, v63
	v_fmac_f32_e32 v71, 0.5, v59
	v_cvt_pk_bf16_f32 v56, v64, v65
	v_cvt_pk_bf16_f32 v57, v66, v67
	v_cvt_pk_bf16_f32 v58, v68, v69
	v_cvt_pk_bf16_f32 v59, v70, v71
	global_load_dwordx4 v[60:63], v[72:73], off offset:256
	v_add_co_u32_e32 v64, vcc, s72, v146
	global_store_dwordx4 v[80:81], v[56:59], off
	s_nop 0
	v_addc_co_u32_e32 v65, vcc, 0, v147, vcc
	s_waitcnt vmcnt(1)
	v_lshlrev_b32_e32 v56, 16, v60
	v_and_b32_e32 v57, 0xffff0000, v60
	v_lshlrev_b32_e32 v58, 16, v61
	v_and_b32_e32 v59, 0xffff0000, v61
	v_lshlrev_b32_e32 v60, 16, v62
	v_and_b32_e32 v61, 0xffff0000, v62
	v_lshlrev_b32_e32 v62, 16, v63
	v_and_b32_e32 v63, 0xffff0000, v63
	v_fmac_f32_e32 v56, 0.5, v52
	v_fmac_f32_e32 v60, 0.5, v48
	v_fmac_f32_e32 v57, 0.5, v53
	v_fmac_f32_e32 v61, 0.5, v49
	v_fmac_f32_e32 v58, 0.5, v54
	v_fmac_f32_e32 v62, 0.5, v50
	v_fmac_f32_e32 v59, 0.5, v55
	v_fmac_f32_e32 v63, 0.5, v51
	v_cvt_pk_bf16_f32 v48, v56, v57
	v_cvt_pk_bf16_f32 v49, v58, v59
	v_cvt_pk_bf16_f32 v50, v60, v61
	v_cvt_pk_bf16_f32 v51, v62, v63
	global_load_dwordx4 v[52:55], v[64:65], off
	v_lshl_add_u64 v[56:57], v[146:147], 0, s[36:37]
	global_store_dwordx4 v[72:73], v[48:51], off offset:256
	s_waitcnt vmcnt(1)
; #define PG8_BAR __builtin_amdgcn_s_barrier()
; __device__ __forceinline__ unsigned pkbf(float lo, float hi) { return pg8::cvt_pk_bf16(lo, hi); }
; __device__ __forceinline__ void unpack8bf(const u32x4 w, float* f) { f[0] = bflo(w.x); f[1] = bfhi(w.x); f[2] = bflo(w.y); f[3] = bfhi(w.y); f[4] = bflo(w.z); f[5] = bfhi(w.z); f[6] = bflo(w.w); f[7] = bfhi(w.w); }
; template <class Epi, class Sched, bool ALIGN_EPI = false, bool SP2 = false>
; __device__ __forceinline__ void gemm_phase(PG8_LAS unsigned char* lds, const Gemm g, const Sched& S, const Epi& E) {
;     ...
;         if (!has_next) break;
; #pragma unroll
;         for (int a = 0; a < 2; ++a)
; #pragma unroll
;             for (int b = 0; b < 2; ++b)
; #pragma unroll
;                 for (int m = 0; m < 4; ++m)
; #pragma unroll
;                     for (int n = 0; n < 2; ++n) acc[a][b][m][n] = (f32x4){0.f, 0.f, 0.f, 0.f};
;         cur = nxt; cA = nA; cB = nB; ++ui;
;         if constexpr (ALIGN_EPI) { if (wr == 1) PG8_BAR; }
;     __device__ __forceinline__ void operator()(AccRef acc, const Unit& u, int wr, int wc, int fr, int fq) const {
;     ...
;                 for (int bj = 0; bj < 2; ++bj) {
;                     const size_t off = (size_t)(row0 + ai * 128 + m * 16) * DM + col0 + bj * 128;
;                     const u32x4 hw = *(const u32x4*)(Hb + off); float h[8]; unpack8bf(hw, h);
; #pragma unroll
;                     for (int e = 0; e < 4; ++e) { h[e] += 0.5f * acc[ai][bj][m][0][e]; h[4 + e] += 0.5f * acc[ai][bj][m][1][e]; }
;                     u32x4 w; w.x = pkbf(h[0], h[1]); w.y = pkbf(h[2], h[3]); w.z = pkbf(h[4], h[5]); w.w = pkbf(h[6], h[7]);
;                     *(u32x4*)(Hb + off) = w;
;                 }
	s_nop 0
	v_lshlrev_b32_e32 v48, 16, v52
	v_and_b32_e32 v49, 0xffff0000, v52
	v_lshlrev_b32_e32 v50, 16, v53
	v_and_b32_e32 v51, 0xffff0000, v53
	v_lshlrev_b32_e32 v52, 16, v54
	v_and_b32_e32 v53, 0xffff0000, v54
	v_lshlrev_b32_e32 v54, 16, v55
	v_and_b32_e32 v55, 0xffff0000, v55
	v_fmac_f32_e32 v48, 0.5, v44
	v_fmac_f32_e32 v52, 0.5, v40
	v_fmac_f32_e32 v49, 0.5, v45
	v_fmac_f32_e32 v53, 0.5, v41
	v_fmac_f32_e32 v50, 0.5, v46
	v_fmac_f32_e32 v54, 0.5, v42
	v_fmac_f32_e32 v51, 0.5, v47
	v_fmac_f32_e32 v55, 0.5, v43
	v_cvt_pk_bf16_f32 v40, v48, v49
	v_cvt_pk_bf16_f32 v41, v50, v51
	v_cvt_pk_bf16_f32 v42, v52, v53
	v_cvt_pk_bf16_f32 v43, v54, v55
	global_load_dwordx4 v[44:47], v[56:57], off offset:256
	v_add_co_u32_e32 v48, vcc, s73, v146
	global_store_dwordx4 v[64:65], v[40:43], off
	s_nop 0
	v_addc_co_u32_e32 v49, vcc, 0, v147, vcc
	s_waitcnt vmcnt(1)
	v_lshlrev_b32_e32 v40, 16, v44
	v_and_b32_e32 v41, 0xffff0000, v44
	v_lshlrev_b32_e32 v42, 16, v45
	v_and_b32_e32 v43, 0xffff0000, v45
	v_lshlrev_b32_e32 v44, 16, v46
	v_and_b32_e32 v45, 0xffff0000, v46
	v_lshlrev_b32_e32 v46, 16, v47
	v_and_b32_e32 v47, 0xffff0000, v47
	v_fmac_f32_e32 v40, 0.5, v36
	v_fmac_f32_e32 v44, 0.5, v32
	v_fmac_f32_e32 v41, 0.5, v37
	v_fmac_f32_e32 v45, 0.5, v33
	v_fmac_f32_e32 v42, 0.5, v38
	v_fmac_f32_e32 v46, 0.5, v34
	v_fmac_f32_e32 v43, 0.5, v39
	v_fmac_f32_e32 v47, 0.5, v35
	v_cvt_pk_bf16_f32 v32, v40, v41
	v_cvt_pk_bf16_f32 v33, v42, v43
	v_cvt_pk_bf16_f32 v34, v44, v45
	v_cvt_pk_bf16_f32 v35, v46, v47
	global_load_dwordx4 v[36:39], v[48:49], off
	v_lshl_add_u64 v[40:41], v[146:147], 0, s[38:39]
	global_store_dwordx4 v[56:57], v[32:35], off offset:256
	s_waitcnt vmcnt(1)
	s_nop 0
	v_lshlrev_b32_e32 v32, 16, v36
	v_and_b32_e32 v33, 0xffff0000, v36
	v_lshlrev_b32_e32 v34, 16, v37
	v_and_b32_e32 v35, 0xffff0000, v37
	v_lshlrev_b32_e32 v36, 16, v38
	v_and_b32_e32 v37, 0xffff0000, v38
	v_lshlrev_b32_e32 v38, 16, v39
	v_and_b32_e32 v39, 0xffff0000, v39
	v_fmac_f32_e32 v32, 0.5, v28
	v_fmac_f32_e32 v36, 0.5, v24
	v_fmac_f32_e32 v33, 0.5, v29
	v_fmac_f32_e32 v37, 0.5, v25
	v_fmac_f32_e32 v34, 0.5, v30
	v_fmac_f32_e32 v38, 0.5, v26
	v_fmac_f32_e32 v35, 0.5, v31
	v_fmac_f32_e32 v39, 0.5, v27
	v_cvt_pk_bf16_f32 v24, v32, v33
	v_cvt_pk_bf16_f32 v25, v34, v35
	v_cvt_pk_bf16_f32 v26, v36, v37
	v_cvt_pk_bf16_f32 v27, v38, v39
	global_load_dwordx4 v[28:31], v[40:41], off offset:256
	v_add_co_u32_e32 v32, vcc, s74, v146
	global_store_dwordx4 v[48:49], v[24:27], off
	s_nop 0
	v_addc_co_u32_e32 v33, vcc, 0, v147, vcc
	s_and_b64 vcc, exec, s[4:5]
	s_mov_b64 s[4:5], -1
	s_waitcnt vmcnt(1)
	v_lshlrev_b32_e32 v24, 16, v28
	v_and_b32_e32 v25, 0xffff0000, v28
	v_lshlrev_b32_e32 v26, 16, v29
	v_and_b32_e32 v27, 0xffff0000, v29
	v_lshlrev_b32_e32 v28, 16, v30
	v_and_b32_e32 v29, 0xffff0000, v30
	v_lshlrev_b32_e32 v30, 16, v31
	v_and_b32_e32 v31, 0xffff0000, v31
	v_fmac_f32_e32 v24, 0.5, v20
	v_fmac_f32_e32 v28, 0.5, v16
	v_fmac_f32_e32 v25, 0.5, v21
	v_fmac_f32_e32 v29, 0.5, v17
	v_fmac_f32_e32 v26, 0.5, v22
	v_fmac_f32_e32 v30, 0.5, v18
	v_fmac_f32_e32 v27, 0.5, v23
	v_fmac_f32_e32 v31, 0.5, v19
	v_cvt_pk_bf16_f32 v16, v24, v25
	v_cvt_pk_bf16_f32 v17, v26, v27
	v_cvt_pk_bf16_f32 v18, v28, v29
	v_cvt_pk_bf16_f32 v19, v30, v31
	global_load_dwordx4 v[20:23], v[32:33], off
	v_lshl_add_u64 v[24:25], v[146:147], 0, s[40:41]
	global_store_dwordx4 v[40:41], v[16:19], off offset:256
	s_waitcnt vmcnt(1)
	s_nop 0
	v_lshlrev_b32_e32 v16, 16, v20
	v_and_b32_e32 v17, 0xffff0000, v20
	v_lshlrev_b32_e32 v18, 16, v21
	v_and_b32_e32 v19, 0xffff0000, v21
	v_lshlrev_b32_e32 v20, 16, v22
	v_and_b32_e32 v21, 0xffff0000, v22
	v_lshlrev_b32_e32 v22, 16, v23
	v_and_b32_e32 v23, 0xffff0000, v23
	v_fmac_f32_e32 v16, 0.5, v12
	v_fmac_f32_e32 v20, 0.5, v8
	v_fmac_f32_e32 v17, 0.5, v13
	v_fmac_f32_e32 v21, 0.5, v9
	v_fmac_f32_e32 v18, 0.5, v14
	v_fmac_f32_e32 v22, 0.5, v10
	v_fmac_f32_e32 v19, 0.5, v15
	v_fmac_f32_e32 v23, 0.5, v11
	v_cvt_pk_bf16_f32 v8, v16, v17
	v_cvt_pk_bf16_f32 v9, v18, v19
	v_cvt_pk_bf16_f32 v10, v20, v21
	v_cvt_pk_bf16_f32 v11, v22, v23
	global_load_dwordx4 v[12:15], v[24:25], off offset:256
	s_nop 0
	global_store_dwordx4 v[32:33], v[8:11], off
	s_waitcnt vmcnt(1)
	s_nop 0
	v_lshlrev_b32_e32 v8, 16, v12
	v_and_b32_e32 v9, 0xffff0000, v12
	v_lshlrev_b32_e32 v10, 16, v13
	v_and_b32_e32 v11, 0xffff0000, v13
	v_lshlrev_b32_e32 v12, 16, v14
	v_and_b32_e32 v13, 0xffff0000, v14
	v_lshlrev_b32_e32 v14, 16, v15
	v_and_b32_e32 v15, 0xffff0000, v15
	v_fmac_f32_e32 v8, 0.5, v4
	v_fmac_f32_e32 v12, 0.5, v0
	v_fmac_f32_e32 v9, 0.5, v5
	v_fmac_f32_e32 v13, 0.5, v1
	v_fmac_f32_e32 v10, 0.5, v6
	v_fmac_f32_e32 v14, 0.5, v2
	v_fmac_f32_e32 v11, 0.5, v7
	v_fmac_f32_e32 v15, 0.5, v3
	v_cvt_pk_bf16_f32 v0, v8, v9
	v_cvt_pk_bf16_f32 v1, v10, v11
	v_cvt_pk_bf16_f32 v2, v12, v13
	v_cvt_pk_bf16_f32 v3, v14, v15
	global_store_dwordx4 v[24:25], v[0:3], off offset:256
	s_cbranch_vccnz .LBB0_1431
	s_andn2_b64 vcc, exec, s[10:11]
	s_cbranch_vccnz .LBB0_1430
	s_barrier
	s_branch .LBB0_1430
